# norm phase: the 12 gamma/shift/scale loads of a row issued together (one wait) instead of one round trip per column group
# speedup vs baseline: 1.1083x; 1.0203x over previous
; __device__ __forceinline__ unsigned cvt_pk_bf16(float lo, float hi) { unsigned r; asm("v_cvt_pk_bf16_f32 %0, %1, %2" : "=v"(r) : "v"(lo), "v"(hi)); return r; }
; __device__ __forceinline__ void phase_norm(PP P, int l, int which, int nsl, const float* fgate, float fscale, const Ids I) {
;     ...
;         for (int j = 0; j < 2; ++j) { float a = 0.f;
; #pragma unroll
;             for (int i = 0; i < 4; ++i) a += v[j][i][0] * v[j][i][0] + v[j][i][1] * v[j][i][1] + v[j][i][2] * v[j][i][2] + v[j][i][3] * v[j][i][3];
;             ss[j] = wave_sum(a); }
; #pragma unroll
;         for (int j = 0; j < 2; ++j) { const int row = rows[j];
;             if (j == 1 && row == row0) continue;
;             const float rstd = rsqrtf(ss[j] * (1.0f / 1024.0f) + 1e-6f);
;             if (which == 3) {
; #pragma unroll
;                 for (int i = 0; i < 4; ++i) { const int col = lane * 4 + 256 * i; const f32x4 g4 = *(const f32x4*)(gamma + col); *(f32x4*)(xb + (size_t)row * D + col) = v[j][i] * rstd * g4; }
;             } else {
;                 const float* mr = modl + (size_t)mod_row(row) * 9216 + which * 3 * 1024;
; #pragma unroll
;                 for (int i = 0; i < 4; ++i) { const int col = lane * 4 + 256 * i; const f32x4 g4 = *(const f32x4*)(gamma + col), sh = *(const f32x4*)(mr + col), sc = *(const f32x4*)(mr + 1024 + col);
;                     const f32x4 h = (v[j][i] * rstd * g4) * (sc + 1.0f) + sh; u32x2 w; w.x = cvt_pk_bf16(h[0], h[1]); w.y = cvt_pk_bf16(h[2], h[3]);
;                     *(u32x2*)(hb + (size_t)row * D + col) = w;
;                     if (from_in) *(f32x4*)(xb + (size_t)row * D + col) = v[j][i]; }
.LBB0_574:
	s_waitcnt vmcnt(0)
	v_mov_b32_e32 v34, v13
	v_mov_b32_e32 v35, v21
	v_mov_b32_e32 v32, v12
	v_mov_b32_e32 v33, v20
	v_pk_mul_f32 v[34:35], v[34:35], v[34:35]
	v_mov_b32_e32 v36, v1
	v_pk_fma_f32 v[32:33], v[32:33], v[32:33], v[34:35]
	v_mov_b32_e32 v34, v14
	v_mov_b32_e32 v35, v22
	v_pk_fma_f32 v[32:33], v[34:35], v[34:35], v[32:33]
	v_mov_b32_e32 v34, v15
	v_mov_b32_e32 v35, v23
	v_mov_b32_e32 v37, v5
	v_pk_fma_f32 v[32:33], v[34:35], v[34:35], v[32:33]
	v_mov_b32_e32 v34, v0
	v_mov_b32_e32 v35, v4
	v_pk_mul_f32 v[36:37], v[36:37], v[36:37]
	v_add_f32_e32 v32, v32, v33
	v_pk_fma_f32 v[34:35], v[34:35], v[34:35], v[36:37]
	v_mov_b32_e32 v36, v2
	v_mov_b32_e32 v37, v6
	v_pk_fma_f32 v[34:35], v[36:37], v[36:37], v[34:35]
	v_mov_b32_e32 v36, v3
	v_mov_b32_e32 v37, v7
	v_pk_fma_f32 v[34:35], v[36:37], v[36:37], v[34:35]
	v_mul_f32_e32 v33, v25, v25
	v_add_f32_e32 v32, v35, v32
	v_add_f32_e32 v32, v34, v32
	v_fmac_f32_e32 v33, v24, v24
	v_fmac_f32_e32 v33, v26, v26
	v_add_f32_dpp v32, v32, v32 quad_perm:[1,0,3,2] row_mask:0xf bank_mask:0xf bound_ctrl:1
	v_fmac_f32_e32 v33, v27, v27
	s_nop 0
	v_add_f32_dpp v32, v32, v32 quad_perm:[2,3,0,1] row_mask:0xf bank_mask:0xf bound_ctrl:1
	s_nop 1
	v_add_f32_dpp v32, v32, v32 row_half_mirror row_mask:0xf bank_mask:0xf bound_ctrl:1
	s_nop 1
	v_add_f32_dpp v32, v32, v32 row_mirror row_mask:0xf bank_mask:0xf bound_ctrl:1
	s_nop 0
	v_readlane_b32 s4, v32, 0
	v_readlane_b32 s9, v32, 16
	v_readlane_b32 s5, v32, 32
	v_readlane_b32 s24, v32, 48
	v_mul_f32_e32 v32, v29, v29
	v_fmac_f32_e32 v32, v28, v28
	v_fmac_f32_e32 v32, v30, v30
	v_fmac_f32_e32 v32, v31, v31
	v_add_f32_e32 v32, v33, v32
	v_mul_f32_e32 v33, v17, v17
	v_fmac_f32_e32 v33, v16, v16
	v_fmac_f32_e32 v33, v18, v18
	v_fmac_f32_e32 v33, v19, v19
	v_add_f32_e32 v32, v33, v32
	v_mul_f32_e32 v33, v9, v9
	v_fmac_f32_e32 v33, v8, v8
	v_fmac_f32_e32 v33, v10, v10
	v_fmac_f32_e32 v33, v11, v11
	v_add_f32_e32 v32, v33, v32
	v_mov_b32_e32 v33, s24
	s_nop 0
	v_add_f32_dpp v32, v32, v32 quad_perm:[1,0,3,2] row_mask:0xf bank_mask:0xf bound_ctrl:1
	s_nop 1
	v_add_f32_dpp v32, v32, v32 quad_perm:[2,3,0,1] row_mask:0xf bank_mask:0xf bound_ctrl:1
	s_nop 1
	v_add_f32_dpp v32, v32, v32 row_half_mirror row_mask:0xf bank_mask:0xf bound_ctrl:1
	s_nop 1
	v_add_f32_dpp v32, v32, v32 row_mirror row_mask:0xf bank_mask:0xf bound_ctrl:1
	s_nop 0
	v_readlane_b32 s17, v32, 0
	v_readlane_b32 s34, v32, 16
	v_readlane_b32 s19, v32, 32
	v_readlane_b32 s35, v32, 48
	v_mov_b32_e32 v32, s9
	v_pk_add_f32 v[32:33], s[4:5], v[32:33]
	s_add_i32 s5, s8, 0xffffc000
	v_add_f32_e32 v32, v32, v33
	v_fmamk_f32 v32, v32, 0x3a800000, v174
	s_lshr_b32 s5, s5, 2
	v_cmp_gt_f32_e32 vcc, s58, v32
	v_mul_f32_e32 v33, 0x4b800000, v32
	s_ashr_i32 s4, s8, 11
	s_add_i32 s5, s5, 8
	v_cndmask_b32_e32 v32, v32, v33, vcc
	s_cmpk_lt_i32 s8, 0x4000
	v_rsq_f32_e32 v32, v32
	s_cselect_b32 s4, s4, s5
	s_mul_hi_i32 s5, s4, 0x9000
	s_mul_i32 s4, s4, 0x9000
	s_add_u32 s28, s30, s4
	s_addc_u32 s29, s31, s5
	v_mul_f32_e32 v33, 0x45800000, v32
	s_add_u32 s26, s28, 0x1000
	v_cndmask_b32_e32 v74, v32, v33, vcc
	s_addc_u32 s27, s29, 0
	global_load_dwordx4 v[84:87], v[56:57], off
	global_load_dwordx4 v[100:103], v144, s[28:29]
	global_load_dwordx4 v[188:191], v144, s[26:27]
	global_load_dwordx4 v[88:91], v[56:57], off offset:1024
	global_load_dwordx4 v[104:107], v144, s[28:29] offset:1024
	global_load_dwordx4 v[192:195], v144, s[26:27] offset:1024
	global_load_dwordx4 v[92:95], v[56:57], off offset:2048
	global_load_dwordx4 v[108:111], v144, s[28:29] offset:2048
	global_load_dwordx4 v[196:199], v144, s[26:27] offset:2048
	global_load_dwordx4 v[96:99], v[56:57], off offset:3072
	global_load_dwordx4 v[112:115], v144, s[28:29] offset:3072
	global_load_dwordx4 v[200:203], v144, s[26:27] offset:3072
	s_ashr_i32 s9, s8, 31
	s_lshl_b64 s[4:5], s[8:9], 12
	s_add_u32 s24, s6, s4
	s_addc_u32 s25, s7, s5
	s_lshl_b64 s[4:5], s[8:9], 11
	v_lshl_add_u64 v[32:33], v[64:65], 0, s[4:5]
	v_cndmask_b32_e64 v34, 0, 1, s[10:11]
	v_mov_b32_e32 v75, v74
	v_cmp_ne_u32_e64 s[4:5], 1, v34
	s_waitcnt vmcnt(0)
	v_pk_mul_f32 v[204:205], v[22:23], v[74:75]
	v_pk_mul_f32 v[206:207], v[20:21], v[74:75]
	v_pk_add_f32 v[190:191], v[190:191], 1.0 op_sel_hi:[1,0]
	v_pk_add_f32 v[188:189], v[188:189], 1.0 op_sel_hi:[1,0]
	v_pk_mul_f32 v[204:205], v[204:205], v[86:87]
	v_pk_mul_f32 v[206:207], v[206:207], v[84:85]
	v_pk_fma_f32 v[204:205], v[204:205], v[190:191], v[102:103]
	v_pk_fma_f32 v[206:207], v[206:207], v[188:189], v[100:101]
	v_cvt_pk_bf16_f32 v208, v206, v207
	v_cvt_pk_bf16_f32 v209, v204, v205
	global_store_dwordx2 v[32:33], v[208:209], off
	v_pk_mul_f32 v[204:205], v[14:15], v[74:75]
	v_pk_mul_f32 v[206:207], v[12:13], v[74:75]
	v_pk_add_f32 v[194:195], v[194:195], 1.0 op_sel_hi:[1,0]
	v_pk_add_f32 v[192:193], v[192:193], 1.0 op_sel_hi:[1,0]
	v_pk_mul_f32 v[204:205], v[204:205], v[90:91]
	v_pk_mul_f32 v[206:207], v[206:207], v[88:89]
	v_pk_fma_f32 v[204:205], v[204:205], v[194:195], v[106:107]
	v_pk_fma_f32 v[206:207], v[206:207], v[192:193], v[104:105]
	v_cvt_pk_bf16_f32 v210, v206, v207
	v_cvt_pk_bf16_f32 v211, v204, v205
	global_store_dwordx2 v[32:33], v[210:211], off offset:512
	v_pk_mul_f32 v[204:205], v[6:7], v[74:75]
	v_pk_mul_f32 v[206:207], v[4:5], v[74:75]
	v_pk_add_f32 v[198:199], v[198:199], 1.0 op_sel_hi:[1,0]
	v_pk_add_f32 v[196:197], v[196:197], 1.0 op_sel_hi:[1,0]
	v_pk_mul_f32 v[204:205], v[204:205], v[94:95]
	v_pk_mul_f32 v[206:207], v[206:207], v[92:93]
	v_pk_fma_f32 v[204:205], v[204:205], v[198:199], v[110:111]
	v_pk_fma_f32 v[206:207], v[206:207], v[196:197], v[108:109]
	v_cvt_pk_bf16_f32 v208, v206, v207
	v_cvt_pk_bf16_f32 v209, v204, v205
	global_store_dwordx2 v[32:33], v[208:209], off offset:1024
	v_pk_mul_f32 v[204:205], v[2:3], v[74:75]
	v_pk_mul_f32 v[206:207], v[0:1], v[74:75]
	v_pk_add_f32 v[202:203], v[202:203], 1.0 op_sel_hi:[1,0]
	v_pk_add_f32 v[200:201], v[200:201], 1.0 op_sel_hi:[1,0]
	v_pk_mul_f32 v[204:205], v[204:205], v[98:99]
	v_pk_mul_f32 v[206:207], v[206:207], v[96:97]
	v_pk_fma_f32 v[204:205], v[204:205], v[202:203], v[114:115]
	v_pk_fma_f32 v[206:207], v[206:207], v[200:201], v[112:113]
	v_cvt_pk_bf16_f32 v210, v206, v207
	v_cvt_pk_bf16_f32 v211, v204, v205
	global_store_dwordx2 v[32:33], v[210:211], off offset:1536
	s_and_b64 vcc, exec, s[4:5]
	s_cbranch_vccnz .Lnrow0_noxb
	global_store_dwordx4 v144, v[20:23], s[24:25]
	global_store_dwordx4 v144, v[12:15], s[24:25] offset:1024
	global_store_dwordx4 v144, v[4:7], s[24:25] offset:2048
	global_store_dwordx4 v144, v[0:3], s[24:25] offset:3072

; __device__ __forceinline__ unsigned cvt_pk_bf16(float lo, float hi) { unsigned r; asm("v_cvt_pk_bf16_f32 %0, %1, %2" : "=v"(r) : "v"(lo), "v"(hi)); return r; }
; __device__ __forceinline__ void phase_norm(PP P, int l, int which, int nsl, const float* fgate, float fscale, const Ids I) {
;     ...
;         for (int j = 0; j < 2; ++j) { const int row = rows[j];
;             if (j == 1 && row == row0) continue;
;             const float rstd = rsqrtf(ss[j] * (1.0f / 1024.0f) + 1e-6f);
;             if (which == 3) {
; #pragma unroll
;                 for (int i = 0; i < 4; ++i) { const int col = lane * 4 + 256 * i; const f32x4 g4 = *(const f32x4*)(gamma + col); *(f32x4*)(xb + (size_t)row * D + col) = v[j][i] * rstd * g4; }
;             } else {
;                 const float* mr = modl + (size_t)mod_row(row) * 9216 + which * 3 * 1024;
; #pragma unroll
;                 for (int i = 0; i < 4; ++i) { const int col = lane * 4 + 256 * i; const f32x4 g4 = *(const f32x4*)(gamma + col), sh = *(const f32x4*)(mr + col), sc = *(const f32x4*)(mr + 1024 + col);
;                     const f32x4 h = (v[j][i] * rstd * g4) * (sc + 1.0f) + sh; u32x2 w; w.x = cvt_pk_bf16(h[0], h[1]); w.y = cvt_pk_bf16(h[2], h[3]);
;                     *(u32x2*)(hb + (size_t)row * D + col) = w;
;                     if (from_in) *(f32x4*)(xb + (size_t)row * D + col) = v[j][i]; }
.LBB0_583:
	v_mov_b32_e32 v0, s34
	v_add_f32_e32 v0, s17, v0
	s_add_i32 s17, s18, 0xffffc000
	s_lshr_b32 s17, s17, 2
	s_ashr_i32 s9, s18, 11
	s_add_i32 s17, s17, 8
	s_and_b64 s[20:21], s[20:21], exec
	s_cselect_b32 s9, s9, s17
	s_mul_hi_i32 s17, s9, 0x9000
	s_mul_i32 s9, s9, 0x9000
	s_add_u32 s24, s30, s9
	s_addc_u32 s25, s31, s17
	s_add_u32 s22, s24, 0x1000
	s_addc_u32 s23, s25, 0
	global_load_dwordx4 v[84:87], v[56:57], off
	global_load_dwordx4 v[100:103], v144, s[24:25]
	global_load_dwordx4 v[188:191], v144, s[22:23]
	global_load_dwordx4 v[88:91], v[56:57], off offset:1024
	global_load_dwordx4 v[104:107], v144, s[24:25] offset:1024
	global_load_dwordx4 v[192:195], v144, s[22:23] offset:1024
	global_load_dwordx4 v[92:95], v[56:57], off offset:2048
	global_load_dwordx4 v[108:111], v144, s[24:25] offset:2048
	global_load_dwordx4 v[196:199], v144, s[22:23] offset:2048
	global_load_dwordx4 v[96:99], v[56:57], off offset:3072
	global_load_dwordx4 v[112:115], v144, s[24:25] offset:3072
	global_load_dwordx4 v[200:203], v144, s[22:23] offset:3072
	v_mov_b32_e32 v1, s35
	v_add_f32_e32 v1, s19, v1
	v_add_f32_e32 v0, v0, v1
	v_fmamk_f32 v0, v0, 0x3a800000, v174
	v_cmp_gt_f32_e32 vcc, s58, v0
	v_mul_f32_e32 v1, 0x4b800000, v0
	s_ashr_i32 s19, s18, 31
	v_cndmask_b32_e32 v0, v0, v1, vcc
	v_rsq_f32_e32 v0, v0
	s_lshl_b64 s[20:21], s[18:19], 12
	s_add_u32 s20, s6, s20
	s_addc_u32 s21, s7, s21
	v_mul_f32_e32 v1, 0x45800000, v0
	v_cndmask_b32_e32 v0, v0, v1, vcc
	s_lshl_b64 s[18:19], s[18:19], 11
	v_lshl_add_u64 v[2:3], v[64:65], 0, s[18:19]
	v_mov_b32_e32 v1, v0
	s_waitcnt vmcnt(0)
	v_pk_mul_f32 v[204:205], v[30:31], v[0:1]
	v_pk_mul_f32 v[206:207], v[28:29], v[0:1]
	v_pk_add_f32 v[190:191], v[190:191], 1.0 op_sel_hi:[1,0]
	v_pk_add_f32 v[188:189], v[188:189], 1.0 op_sel_hi:[1,0]
	v_pk_mul_f32 v[204:205], v[204:205], v[86:87]
	v_pk_mul_f32 v[206:207], v[206:207], v[84:85]
	v_pk_fma_f32 v[204:205], v[204:205], v[190:191], v[102:103]
	v_pk_fma_f32 v[206:207], v[206:207], v[188:189], v[100:101]
	v_cvt_pk_bf16_f32 v208, v206, v207
	v_cvt_pk_bf16_f32 v209, v204, v205
	global_store_dwordx2 v[2:3], v[208:209], off
	v_pk_mul_f32 v[204:205], v[26:27], v[0:1]
	v_pk_mul_f32 v[206:207], v[24:25], v[0:1]
	v_pk_add_f32 v[194:195], v[194:195], 1.0 op_sel_hi:[1,0]
	v_pk_add_f32 v[192:193], v[192:193], 1.0 op_sel_hi:[1,0]
	v_pk_mul_f32 v[204:205], v[204:205], v[90:91]
	v_pk_mul_f32 v[206:207], v[206:207], v[88:89]
	v_pk_fma_f32 v[204:205], v[204:205], v[194:195], v[106:107]
	v_pk_fma_f32 v[206:207], v[206:207], v[192:193], v[104:105]
	v_cvt_pk_bf16_f32 v210, v206, v207
	v_cvt_pk_bf16_f32 v211, v204, v205
	global_store_dwordx2 v[2:3], v[210:211], off offset:512
	v_pk_mul_f32 v[204:205], v[18:19], v[0:1]
	v_pk_mul_f32 v[206:207], v[16:17], v[0:1]
	v_pk_add_f32 v[198:199], v[198:199], 1.0 op_sel_hi:[1,0]
	v_pk_add_f32 v[196:197], v[196:197], 1.0 op_sel_hi:[1,0]
	v_pk_mul_f32 v[204:205], v[204:205], v[94:95]
	v_pk_mul_f32 v[206:207], v[206:207], v[92:93]
	v_pk_fma_f32 v[204:205], v[204:205], v[198:199], v[110:111]
	v_pk_fma_f32 v[206:207], v[206:207], v[196:197], v[108:109]
	v_cvt_pk_bf16_f32 v208, v206, v207
	v_cvt_pk_bf16_f32 v209, v204, v205
	global_store_dwordx2 v[2:3], v[208:209], off offset:1024
	v_pk_mul_f32 v[204:205], v[10:11], v[0:1]
	v_pk_mul_f32 v[206:207], v[8:9], v[0:1]
	v_pk_add_f32 v[202:203], v[202:203], 1.0 op_sel_hi:[1,0]
	v_pk_add_f32 v[200:201], v[200:201], 1.0 op_sel_hi:[1,0]
	v_pk_mul_f32 v[204:205], v[204:205], v[98:99]
	v_pk_mul_f32 v[206:207], v[206:207], v[96:97]
	v_pk_fma_f32 v[204:205], v[204:205], v[202:203], v[114:115]
	v_pk_fma_f32 v[206:207], v[206:207], v[200:201], v[112:113]
	v_cvt_pk_bf16_f32 v210, v206, v207
	v_cvt_pk_bf16_f32 v211, v204, v205
	global_store_dwordx2 v[2:3], v[210:211], off offset:1536
	s_and_b64 vcc, exec, s[4:5]
	s_cbranch_vccnz .LBB0_539
	global_store_dwordx4 v144, v[28:31], s[20:21]
	global_store_dwordx4 v144, v[24:27], s[20:21] offset:1024
	global_store_dwordx4 v144, v[16:19], s[20:21] offset:2048
	global_store_dwordx4 v144, v[8:11], s[20:21] offset:3072
	s_branch .LBB0_539
